# MERGE: dedicated straight-line epilogue for the two rescale units; 32 gate loads in flight with counted waits per group; 40 VALU per group instead of 62
# speedup vs baseline: 1.0036x; 1.0036x over previous
; __device__ __forceinline__ u32x4 pack8(f32x4 a, f32x4 b) { u32x4 w; w.x = cvt_pk_bf16(a[0], a[1]); w.y = cvt_pk_bf16(a[2], a[3]); w.z = cvt_pk_bf16(b[0], b[1]); w.w = cvt_pk_bf16(b[2], b[3]); return w; }
;     __device__ __forceinline__ void operator()(Acc& acc, const Unit& u, int wr, int wc, int fr, int fq) const {
;         const int row0 = u.pm * BM + wr * 64 + fr, colb = u.pn * BM + wc * 64 + 8 * fq, j = u.tag;
; #pragma unroll
;         for (int ai = 0; ai < 2; ++ai)
; #pragma unroll
;             for (int m = 0; m < 4; ++m) { const int row = row0 + ai * HALF + m * 16;
; #pragma unroll
;                 for (int bj = 0; bj < 2; ++bj) { const int col = colb + bj * BJ; const unsigned char* gp = gates + (size_t)row * 6144 + j * 2048 + col;
;                     const u32x2 gw = *(const u32x2*)gp; const f32x4 g0 = unpack_gate4(gw.x), g1 = unpack_gate4(gw.y);
;                     if (j < 2) { const u32x2 hw = *(const u32x2*)(gp + 2048); const f32x4 h0 = unpack_gate4(hw.x), h1 = unpack_gate4(hw.y);
; #pragma unroll
;                         for (int e = 0; e < 4; ++e) { acc[ai][bj][m][0][e] *= g0[e] * __builtin_amdgcn_rcpf(fmaxf(h0[e], 1e-30f)); acc[ai][bj][m][1][e] *= g1[e] * __builtin_amdgcn_rcpf(fmaxf(h1[e], 1e-30f)); } }
;                     else *(u32x4*)(O + (size_t)(row >> 1) * 4096 + (size_t)(col >> 5) * 64 + (row & 1) * 32 + (col & 31)) = pack8(acc[ai][bj][m][0] * g0, acc[ai][bj][m][1] * g1); } }
.LBB0_711:
	s_cmp_lt_i32 s10, 2
	s_cbranch_scc1 .Lmg01
	s_lshl_b32 s2, s25, 8
	s_or_b32 s20, s2, s37
	v_lshl_add_u32 v180, s41, 8, v145
	s_lshl_b32 s22, s10, 11
	v_mov_b64_e32 v[154:155], s[74:75]
	s_ashr_i32 s23, s22, 31
	v_or_b32_e32 v160, s20, v142
	v_mad_i64_i32 v[154:155], s[24:25], v180, s49, v[154:155]
	v_lshl_add_u64 v[164:165], v[154:155], 0, s[22:23]
	v_ashrrev_i32_e32 v161, 31, v160
	v_lshl_add_u64 v[174:175], v[164:165], 0, v[160:161]
	global_load_dwordx2 v[154:155], v[174:175], off
	s_mov_b32 s101, 0
	s_cmp_gt_i32 s10, 1
	s_cbranch_scc1 .Lmg_pref_g
	s_mov_b32 s100, 0x18000
	v_lshl_add_u64 v[228:229], v[174:175], 0, s[100:101]
	global_load_dwordx2 v[186:187], v[174:175], off offset:32
	global_load_dwordx2 v[222:223], v[174:175], off offset:2048
	global_load_dwordx2 v[224:225], v[174:175], off offset:2080
	v_lshl_add_u64 v[232:233], v[228:229], 0, s[100:101]
	global_load_dwordx2 v[188:189], v[228:229], off
	global_load_dwordx2 v[190:191], v[228:229], off offset:32
	global_load_dwordx2 v[226:227], v[228:229], off offset:2048
	global_load_dwordx2 v[228:229], v[228:229], off offset:2080
	v_lshl_add_u64 v[236:237], v[232:233], 0, s[100:101]
	global_load_dwordx2 v[192:193], v[232:233], off
	global_load_dwordx2 v[194:195], v[232:233], off offset:32
	global_load_dwordx2 v[230:231], v[232:233], off offset:2048
	global_load_dwordx2 v[232:233], v[232:233], off offset:2080
	s_mov_b32 s100, 0x78000
	v_lshl_add_u64 v[240:241], v[236:237], 0, s[100:101]
	global_load_dwordx2 v[196:197], v[236:237], off
	global_load_dwordx2 v[198:199], v[236:237], off offset:32
	global_load_dwordx2 v[234:235], v[236:237], off offset:2048
	global_load_dwordx2 v[236:237], v[236:237], off offset:2080
	s_mov_b32 s100, 0x18000
	v_lshl_add_u64 v[244:245], v[240:241], 0, s[100:101]
	global_load_dwordx2 v[200:201], v[240:241], off
	global_load_dwordx2 v[202:203], v[240:241], off offset:32
	global_load_dwordx2 v[238:239], v[240:241], off offset:2048
	global_load_dwordx2 v[240:241], v[240:241], off offset:2080
	v_lshl_add_u64 v[246:247], v[244:245], 0, s[100:101]
	global_load_dwordx2 v[204:205], v[244:245], off
	global_load_dwordx2 v[206:207], v[244:245], off offset:32
	global_load_dwordx2 v[242:243], v[244:245], off offset:2048
	global_load_dwordx2 v[244:245], v[244:245], off offset:2080
	v_lshl_add_u64 v[220:221], v[246:247], 0, s[100:101]
	global_load_dwordx2 v[208:209], v[246:247], off
	global_load_dwordx2 v[210:211], v[246:247], off offset:32
	global_load_dwordx2 v[246:247], v[246:247], off offset:2048
	global_load_dwordx2 v[212:213], v[220:221], off
	global_load_dwordx2 v[220:221], v[220:221], off offset:32
	s_branch .Lmg_pref_done

;     __device__ __forceinline__ void operator()(Acc& acc, const Unit& u, int wr, int wc, int fr, int fq) const {
;     ...
;                 for (int bj = 0; bj < 2; ++bj) { const int col = colb + bj * BJ; const unsigned char* gp = gates + (size_t)row * 6144 + j * 2048 + col;
;                     const u32x2 gw = *(const u32x2*)gp; const f32x4 g0 = unpack_gate4(gw.x), g1 = unpack_gate4(gw.y);
;                     if (j < 2) { const u32x2 hw = *(const u32x2*)(gp + 2048); const f32x4 h0 = unpack_gate4(hw.x), h1 = unpack_gate4(hw.y);
; #pragma unroll
;                         for (int e = 0; e < 4; ++e) { acc[ai][bj][m][0][e] *= g0[e] * __builtin_amdgcn_rcpf(fmaxf(h0[e], 1e-30f)); acc[ai][bj][m][1][e] *= g1[e] * __builtin_amdgcn_rcpf(fmaxf(h1[e], 1e-30f)); } }
.Lmg01:
	s_lshl_b32 s2, s25, 8
	s_or_b32 s20, s2, s37
	v_lshl_add_u32 v182, s41, 8, v145
	s_lshl_b32 s22, s10, 11
	v_mov_b64_e32 v[154:155], s[74:75]
	s_ashr_i32 s23, s22, 31
	v_or_b32_e32 v160, s20, v142
	v_mad_i64_i32 v[154:155], s[24:25], v182, s49, v[154:155]
	v_lshl_add_u64 v[164:165], v[154:155], 0, s[22:23]
	v_ashrrev_i32_e32 v161, 31, v160
	v_lshl_add_u64 v[192:193], v[164:165], 0, v[160:161]
	s_mov_b32 s3, 0
	s_mov_b32 s100, 0.5
	s_mov_b32 s101, 0.5
	s_mov_b32 s2, 0x18000
	v_lshl_add_u64 v[200:201], v[192:193], 0, s[2:3]
	global_load_dwordx2 v[186:187], v[192:193], off
	global_load_dwordx2 v[188:189], v[192:193], off offset:2048
	global_load_dwordx2 v[190:191], v[192:193], off offset:32
	global_load_dwordx2 v[192:193], v[192:193], off offset:2080
	v_lshl_add_u64 v[208:209], v[200:201], 0, s[2:3]
	global_load_dwordx2 v[194:195], v[200:201], off
	global_load_dwordx2 v[196:197], v[200:201], off offset:2048
	global_load_dwordx2 v[198:199], v[200:201], off offset:32
	global_load_dwordx2 v[200:201], v[200:201], off offset:2080
	v_lshl_add_u64 v[222:223], v[208:209], 0, s[2:3]
	global_load_dwordx2 v[202:203], v[208:209], off
	global_load_dwordx2 v[204:205], v[208:209], off offset:2048
	global_load_dwordx2 v[206:207], v[208:209], off offset:32
	global_load_dwordx2 v[208:209], v[208:209], off offset:2080
	s_mov_b32 s2, 0x78000
	v_lshl_add_u64 v[230:231], v[222:223], 0, s[2:3]
	global_load_dwordx2 v[210:211], v[222:223], off
	global_load_dwordx2 v[212:213], v[222:223], off offset:2048
	global_load_dwordx2 v[220:221], v[222:223], off offset:32
	global_load_dwordx2 v[222:223], v[222:223], off offset:2080
	s_mov_b32 s2, 0x18000
	v_lshl_add_u64 v[238:239], v[230:231], 0, s[2:3]
	global_load_dwordx2 v[224:225], v[230:231], off
	global_load_dwordx2 v[226:227], v[230:231], off offset:2048
	global_load_dwordx2 v[228:229], v[230:231], off offset:32
	global_load_dwordx2 v[230:231], v[230:231], off offset:2080
	v_lshl_add_u64 v[246:247], v[238:239], 0, s[2:3]
	global_load_dwordx2 v[232:233], v[238:239], off
	global_load_dwordx2 v[234:235], v[238:239], off offset:2048
	global_load_dwordx2 v[236:237], v[238:239], off offset:32
	global_load_dwordx2 v[238:239], v[238:239], off offset:2080
	v_lshl_add_u64 v[180:181], v[246:247], 0, s[2:3]
	global_load_dwordx2 v[240:241], v[246:247], off
	global_load_dwordx2 v[242:243], v[246:247], off offset:2048
	global_load_dwordx2 v[244:245], v[246:247], off offset:32
	global_load_dwordx2 v[246:247], v[246:247], off offset:2080
	global_load_dwordx2 v[172:173], v[180:181], off
	global_load_dwordx2 v[174:175], v[180:181], off offset:2048
	global_load_dwordx2 v[176:177], v[180:181], off offset:32
	global_load_dwordx2 v[180:181], v[180:181], off offset:2080
	s_waitcnt vmcnt(30)
	v_cvt_f32_ubyte0_e32 v164, v188
	v_cvt_f32_ubyte1_e32 v165, v188
	v_cvt_f32_ubyte2_e32 v166, v188
	v_cvt_f32_ubyte3_e32 v167, v188
	v_cvt_f32_ubyte0_e32 v168, v189
	v_cvt_f32_ubyte1_e32 v169, v189
	v_cvt_f32_ubyte2_e32 v170, v189
	v_cvt_f32_ubyte3_e32 v171, v189
	v_pk_add_f32 v[164:165], v[164:165], s[100:101]
	v_pk_add_f32 v[166:167], v[166:167], s[100:101]
	v_pk_add_f32 v[168:169], v[168:169], s[100:101]
	v_pk_add_f32 v[170:171], v[170:171], s[100:101]
	v_cvt_f32_ubyte0_e32 v154, v186
	v_cvt_f32_ubyte1_e32 v155, v186
	v_cvt_f32_ubyte2_e32 v156, v186
	v_cvt_f32_ubyte3_e32 v157, v186
	v_cvt_f32_ubyte0_e32 v160, v187
	v_cvt_f32_ubyte1_e32 v161, v187
	v_cvt_f32_ubyte2_e32 v162, v187
	v_cvt_f32_ubyte3_e32 v163, v187
	v_rcp_f32_e32 v164, v164
	v_rcp_f32_e32 v165, v165
	v_rcp_f32_e32 v166, v166
	v_rcp_f32_e32 v167, v167
	v_rcp_f32_e32 v168, v168
	v_rcp_f32_e32 v169, v169
	v_rcp_f32_e32 v170, v170
	v_rcp_f32_e32 v171, v171
	v_pk_add_f32 v[154:155], v[154:155], s[100:101]
	v_pk_add_f32 v[156:157], v[156:157], s[100:101]
	v_pk_add_f32 v[160:161], v[160:161], s[100:101]
	v_pk_add_f32 v[162:163], v[162:163], s[100:101]
	v_pk_mul_f32 v[154:155], v[154:155], v[164:165]
	v_pk_mul_f32 v[156:157], v[156:157], v[166:167]
	v_pk_mul_f32 v[160:161], v[160:161], v[168:169]
	v_pk_mul_f32 v[162:163], v[162:163], v[170:171]
	v_pk_mul_f32 v[130:131], v[130:131], v[154:155]
	v_pk_mul_f32 v[132:133], v[132:133], v[156:157]
	v_pk_mul_f32 v[126:127], v[126:127], v[160:161]
	v_pk_mul_f32 v[128:129], v[128:129], v[162:163]
	s_waitcnt vmcnt(28)
	v_cvt_f32_ubyte0_e32 v164, v192
	v_cvt_f32_ubyte1_e32 v165, v192
	v_cvt_f32_ubyte2_e32 v166, v192
	v_cvt_f32_ubyte3_e32 v167, v192
	v_cvt_f32_ubyte0_e32 v168, v193
	v_cvt_f32_ubyte1_e32 v169, v193
	v_cvt_f32_ubyte2_e32 v170, v193
	v_cvt_f32_ubyte3_e32 v171, v193
	v_pk_add_f32 v[164:165], v[164:165], s[100:101]
	v_pk_add_f32 v[166:167], v[166:167], s[100:101]
	v_pk_add_f32 v[168:169], v[168:169], s[100:101]
	v_pk_add_f32 v[170:171], v[170:171], s[100:101]
	v_cvt_f32_ubyte0_e32 v154, v190
	v_cvt_f32_ubyte1_e32 v155, v190
	v_cvt_f32_ubyte2_e32 v156, v190
	v_cvt_f32_ubyte3_e32 v157, v190
	v_cvt_f32_ubyte0_e32 v160, v191
	v_cvt_f32_ubyte1_e32 v161, v191
	v_cvt_f32_ubyte2_e32 v162, v191
	v_cvt_f32_ubyte3_e32 v163, v191
	v_rcp_f32_e32 v164, v164
	v_rcp_f32_e32 v165, v165
	v_rcp_f32_e32 v166, v166
	v_rcp_f32_e32 v167, v167
	v_rcp_f32_e32 v168, v168
	v_rcp_f32_e32 v169, v169
	v_rcp_f32_e32 v170, v170
	v_rcp_f32_e32 v171, v171
	v_pk_add_f32 v[154:155], v[154:155], s[100:101]
	v_pk_add_f32 v[156:157], v[156:157], s[100:101]
	v_pk_add_f32 v[160:161], v[160:161], s[100:101]
	v_pk_add_f32 v[162:163], v[162:163], s[100:101]
	v_pk_mul_f32 v[154:155], v[154:155], v[164:165]
	v_pk_mul_f32 v[156:157], v[156:157], v[166:167]
	v_pk_mul_f32 v[160:161], v[160:161], v[168:169]
	v_pk_mul_f32 v[162:163], v[162:163], v[170:171]
	v_pk_mul_f32 v[94:95], v[94:95], v[154:155]
	v_pk_mul_f32 v[96:97], v[96:97], v[156:157]
	v_pk_mul_f32 v[90:91], v[90:91], v[160:161]
	v_pk_mul_f32 v[92:93], v[92:93], v[162:163]
	s_waitcnt vmcnt(26)
;     __device__ __forceinline__ void operator()(Acc& acc, const Unit& u, int wr, int wc, int fr, int fq) const {
;     ...
;                 for (int bj = 0; bj < 2; ++bj) { const int col = colb + bj * BJ; const unsigned char* gp = gates + (size_t)row * 6144 + j * 2048 + col;
;                     const u32x2 gw = *(const u32x2*)gp; const f32x4 g0 = unpack_gate4(gw.x), g1 = unpack_gate4(gw.y);
;                     if (j < 2) { const u32x2 hw = *(const u32x2*)(gp + 2048); const f32x4 h0 = unpack_gate4(hw.x), h1 = unpack_gate4(hw.y);
; #pragma unroll
;                         for (int e = 0; e < 4; ++e) { acc[ai][bj][m][0][e] *= g0[e] * __builtin_amdgcn_rcpf(fmaxf(h0[e], 1e-30f)); acc[ai][bj][m][1][e] *= g1[e] * __builtin_amdgcn_rcpf(fmaxf(h1[e], 1e-30f)); } }
	v_cvt_f32_ubyte0_e32 v164, v196
	v_cvt_f32_ubyte1_e32 v165, v196
	v_cvt_f32_ubyte2_e32 v166, v196
	v_cvt_f32_ubyte3_e32 v167, v196
	v_cvt_f32_ubyte0_e32 v168, v197
	v_cvt_f32_ubyte1_e32 v169, v197
	v_cvt_f32_ubyte2_e32 v170, v197
	v_cvt_f32_ubyte3_e32 v171, v197
	v_pk_add_f32 v[164:165], v[164:165], s[100:101]
	v_pk_add_f32 v[166:167], v[166:167], s[100:101]
	v_pk_add_f32 v[168:169], v[168:169], s[100:101]
	v_pk_add_f32 v[170:171], v[170:171], s[100:101]
	v_cvt_f32_ubyte0_e32 v154, v194
	v_cvt_f32_ubyte1_e32 v155, v194
	v_cvt_f32_ubyte2_e32 v156, v194
	v_cvt_f32_ubyte3_e32 v157, v194
	v_cvt_f32_ubyte0_e32 v160, v195
	v_cvt_f32_ubyte1_e32 v161, v195
	v_cvt_f32_ubyte2_e32 v162, v195
	v_cvt_f32_ubyte3_e32 v163, v195
	v_rcp_f32_e32 v164, v164
	v_rcp_f32_e32 v165, v165
	v_rcp_f32_e32 v166, v166
	v_rcp_f32_e32 v167, v167
	v_rcp_f32_e32 v168, v168
	v_rcp_f32_e32 v169, v169
	v_rcp_f32_e32 v170, v170
	v_rcp_f32_e32 v171, v171
	v_pk_add_f32 v[154:155], v[154:155], s[100:101]
	v_pk_add_f32 v[156:157], v[156:157], s[100:101]
	v_pk_add_f32 v[160:161], v[160:161], s[100:101]
	v_pk_add_f32 v[162:163], v[162:163], s[100:101]
	v_pk_mul_f32 v[154:155], v[154:155], v[164:165]
	v_pk_mul_f32 v[156:157], v[156:157], v[166:167]
	v_pk_mul_f32 v[160:161], v[160:161], v[168:169]
	v_pk_mul_f32 v[162:163], v[162:163], v[170:171]
	v_pk_mul_f32 v[122:123], v[122:123], v[154:155]
	v_pk_mul_f32 v[124:125], v[124:125], v[156:157]
	v_pk_mul_f32 v[118:119], v[118:119], v[160:161]
	v_pk_mul_f32 v[120:121], v[120:121], v[162:163]
	s_waitcnt vmcnt(24)
	v_cvt_f32_ubyte0_e32 v164, v200
	v_cvt_f32_ubyte1_e32 v165, v200
	v_cvt_f32_ubyte2_e32 v166, v200
	v_cvt_f32_ubyte3_e32 v167, v200
	v_cvt_f32_ubyte0_e32 v168, v201
	v_cvt_f32_ubyte1_e32 v169, v201
	v_cvt_f32_ubyte2_e32 v170, v201
	v_cvt_f32_ubyte3_e32 v171, v201
	v_pk_add_f32 v[164:165], v[164:165], s[100:101]
	v_pk_add_f32 v[166:167], v[166:167], s[100:101]
	v_pk_add_f32 v[168:169], v[168:169], s[100:101]
	v_pk_add_f32 v[170:171], v[170:171], s[100:101]
	v_cvt_f32_ubyte0_e32 v154, v198
	v_cvt_f32_ubyte1_e32 v155, v198
	v_cvt_f32_ubyte2_e32 v156, v198
	v_cvt_f32_ubyte3_e32 v157, v198
	v_cvt_f32_ubyte0_e32 v160, v199
	v_cvt_f32_ubyte1_e32 v161, v199
	v_cvt_f32_ubyte2_e32 v162, v199
	v_cvt_f32_ubyte3_e32 v163, v199
	v_rcp_f32_e32 v164, v164
	v_rcp_f32_e32 v165, v165
	v_rcp_f32_e32 v166, v166
	v_rcp_f32_e32 v167, v167
	v_rcp_f32_e32 v168, v168
	v_rcp_f32_e32 v169, v169
	v_rcp_f32_e32 v170, v170
	v_rcp_f32_e32 v171, v171
	v_pk_add_f32 v[154:155], v[154:155], s[100:101]
	v_pk_add_f32 v[156:157], v[156:157], s[100:101]
	v_pk_add_f32 v[160:161], v[160:161], s[100:101]
	v_pk_add_f32 v[162:163], v[162:163], s[100:101]
	v_pk_mul_f32 v[154:155], v[154:155], v[164:165]
	v_pk_mul_f32 v[156:157], v[156:157], v[166:167]
	v_pk_mul_f32 v[160:161], v[160:161], v[168:169]
	v_pk_mul_f32 v[162:163], v[162:163], v[170:171]
	v_pk_mul_f32 v[86:87], v[86:87], v[154:155]
	v_pk_mul_f32 v[88:89], v[88:89], v[156:157]
	v_pk_mul_f32 v[82:83], v[82:83], v[160:161]
	v_pk_mul_f32 v[84:85], v[84:85], v[162:163]
	s_waitcnt vmcnt(22)
	v_cvt_f32_ubyte0_e32 v164, v204
	v_cvt_f32_ubyte1_e32 v165, v204
	v_cvt_f32_ubyte2_e32 v166, v204
	v_cvt_f32_ubyte3_e32 v167, v204
	v_cvt_f32_ubyte0_e32 v168, v205
	v_cvt_f32_ubyte1_e32 v169, v205
	v_cvt_f32_ubyte2_e32 v170, v205
	v_cvt_f32_ubyte3_e32 v171, v205
	v_pk_add_f32 v[164:165], v[164:165], s[100:101]
	v_pk_add_f32 v[166:167], v[166:167], s[100:101]
	v_pk_add_f32 v[168:169], v[168:169], s[100:101]
	v_pk_add_f32 v[170:171], v[170:171], s[100:101]
	v_cvt_f32_ubyte0_e32 v154, v202
	v_cvt_f32_ubyte1_e32 v155, v202
	v_cvt_f32_ubyte2_e32 v156, v202
	v_cvt_f32_ubyte3_e32 v157, v202
	v_cvt_f32_ubyte0_e32 v160, v203
	v_cvt_f32_ubyte1_e32 v161, v203
	v_cvt_f32_ubyte2_e32 v162, v203
	v_cvt_f32_ubyte3_e32 v163, v203
	v_rcp_f32_e32 v164, v164
	v_rcp_f32_e32 v165, v165
	v_rcp_f32_e32 v166, v166
	v_rcp_f32_e32 v167, v167
	v_rcp_f32_e32 v168, v168
	v_rcp_f32_e32 v169, v169
	v_rcp_f32_e32 v170, v170
	v_rcp_f32_e32 v171, v171
	v_pk_add_f32 v[154:155], v[154:155], s[100:101]
	v_pk_add_f32 v[156:157], v[156:157], s[100:101]
	v_pk_add_f32 v[160:161], v[160:161], s[100:101]
	v_pk_add_f32 v[162:163], v[162:163], s[100:101]
	v_pk_mul_f32 v[154:155], v[154:155], v[164:165]
	v_pk_mul_f32 v[156:157], v[156:157], v[166:167]
	v_pk_mul_f32 v[160:161], v[160:161], v[168:169]
	v_pk_mul_f32 v[162:163], v[162:163], v[170:171]
	v_pk_mul_f32 v[114:115], v[114:115], v[154:155]
	v_pk_mul_f32 v[116:117], v[116:117], v[156:157]
	v_pk_mul_f32 v[110:111], v[110:111], v[160:161]
	v_pk_mul_f32 v[112:113], v[112:113], v[162:163]
	s_waitcnt vmcnt(20)
	v_cvt_f32_ubyte0_e32 v164, v208
	v_cvt_f32_ubyte1_e32 v165, v208
	v_cvt_f32_ubyte2_e32 v166, v208
	v_cvt_f32_ubyte3_e32 v167, v208
	v_cvt_f32_ubyte0_e32 v168, v209
	v_cvt_f32_ubyte1_e32 v169, v209
	v_cvt_f32_ubyte2_e32 v170, v209
	v_cvt_f32_ubyte3_e32 v171, v209
	v_pk_add_f32 v[164:165], v[164:165], s[100:101]
	v_pk_add_f32 v[166:167], v[166:167], s[100:101]
	v_pk_add_f32 v[168:169], v[168:169], s[100:101]
	v_pk_add_f32 v[170:171], v[170:171], s[100:101]
	v_cvt_f32_ubyte0_e32 v154, v206
	v_cvt_f32_ubyte1_e32 v155, v206
	v_cvt_f32_ubyte2_e32 v156, v206
	v_cvt_f32_ubyte3_e32 v157, v206
	v_cvt_f32_ubyte0_e32 v160, v207
	v_cvt_f32_ubyte1_e32 v161, v207
	v_cvt_f32_ubyte2_e32 v162, v207
	v_cvt_f32_ubyte3_e32 v163, v207
	v_rcp_f32_e32 v164, v164
	v_rcp_f32_e32 v165, v165
	v_rcp_f32_e32 v166, v166
	v_rcp_f32_e32 v167, v167
	v_rcp_f32_e32 v168, v168
	v_rcp_f32_e32 v169, v169
	v_rcp_f32_e32 v170, v170
	v_rcp_f32_e32 v171, v171
	v_pk_add_f32 v[154:155], v[154:155], s[100:101]
	v_pk_add_f32 v[156:157], v[156:157], s[100:101]
	v_pk_add_f32 v[160:161], v[160:161], s[100:101]
	v_pk_add_f32 v[162:163], v[162:163], s[100:101]
	v_pk_mul_f32 v[154:155], v[154:155], v[164:165]
	v_pk_mul_f32 v[156:157], v[156:157], v[166:167]
	v_pk_mul_f32 v[160:161], v[160:161], v[168:169]
	v_pk_mul_f32 v[162:163], v[162:163], v[170:171]
	v_pk_mul_f32 v[78:79], v[78:79], v[154:155]
	v_pk_mul_f32 v[80:81], v[80:81], v[156:157]
	v_pk_mul_f32 v[74:75], v[74:75], v[160:161]
	v_pk_mul_f32 v[76:77], v[76:77], v[162:163]
	s_waitcnt vmcnt(18)
;     __device__ __forceinline__ void operator()(Acc& acc, const Unit& u, int wr, int wc, int fr, int fq) const {
;     ...
;                 for (int bj = 0; bj < 2; ++bj) { const int col = colb + bj * BJ; const unsigned char* gp = gates + (size_t)row * 6144 + j * 2048 + col;
;                     const u32x2 gw = *(const u32x2*)gp; const f32x4 g0 = unpack_gate4(gw.x), g1 = unpack_gate4(gw.y);
;                     if (j < 2) { const u32x2 hw = *(const u32x2*)(gp + 2048); const f32x4 h0 = unpack_gate4(hw.x), h1 = unpack_gate4(hw.y);
; #pragma unroll
;                         for (int e = 0; e < 4; ++e) { acc[ai][bj][m][0][e] *= g0[e] * __builtin_amdgcn_rcpf(fmaxf(h0[e], 1e-30f)); acc[ai][bj][m][1][e] *= g1[e] * __builtin_amdgcn_rcpf(fmaxf(h1[e], 1e-30f)); } }
	v_cvt_f32_ubyte0_e32 v164, v212
	v_cvt_f32_ubyte1_e32 v165, v212
	v_cvt_f32_ubyte2_e32 v166, v212
	v_cvt_f32_ubyte3_e32 v167, v212
	v_cvt_f32_ubyte0_e32 v168, v213
	v_cvt_f32_ubyte1_e32 v169, v213
	v_cvt_f32_ubyte2_e32 v170, v213
	v_cvt_f32_ubyte3_e32 v171, v213
	v_pk_add_f32 v[164:165], v[164:165], s[100:101]
	v_pk_add_f32 v[166:167], v[166:167], s[100:101]
	v_pk_add_f32 v[168:169], v[168:169], s[100:101]
	v_pk_add_f32 v[170:171], v[170:171], s[100:101]
	v_cvt_f32_ubyte0_e32 v154, v210
	v_cvt_f32_ubyte1_e32 v155, v210
	v_cvt_f32_ubyte2_e32 v156, v210
	v_cvt_f32_ubyte3_e32 v157, v210
	v_cvt_f32_ubyte0_e32 v160, v211
	v_cvt_f32_ubyte1_e32 v161, v211
	v_cvt_f32_ubyte2_e32 v162, v211
	v_cvt_f32_ubyte3_e32 v163, v211
	v_rcp_f32_e32 v164, v164
	v_rcp_f32_e32 v165, v165
	v_rcp_f32_e32 v166, v166
	v_rcp_f32_e32 v167, v167
	v_rcp_f32_e32 v168, v168
	v_rcp_f32_e32 v169, v169
	v_rcp_f32_e32 v170, v170
	v_rcp_f32_e32 v171, v171
	v_pk_add_f32 v[154:155], v[154:155], s[100:101]
	v_pk_add_f32 v[156:157], v[156:157], s[100:101]
	v_pk_add_f32 v[160:161], v[160:161], s[100:101]
	v_pk_add_f32 v[162:163], v[162:163], s[100:101]
	v_pk_mul_f32 v[154:155], v[154:155], v[164:165]
	v_pk_mul_f32 v[156:157], v[156:157], v[166:167]
	v_pk_mul_f32 v[160:161], v[160:161], v[168:169]
	v_pk_mul_f32 v[162:163], v[162:163], v[170:171]
	v_pk_mul_f32 v[106:107], v[106:107], v[154:155]
	v_pk_mul_f32 v[108:109], v[108:109], v[156:157]
	v_pk_mul_f32 v[102:103], v[102:103], v[160:161]
	v_pk_mul_f32 v[104:105], v[104:105], v[162:163]
	s_waitcnt vmcnt(16)
	v_cvt_f32_ubyte0_e32 v164, v222
	v_cvt_f32_ubyte1_e32 v165, v222
	v_cvt_f32_ubyte2_e32 v166, v222
	v_cvt_f32_ubyte3_e32 v167, v222
	v_cvt_f32_ubyte0_e32 v168, v223
	v_cvt_f32_ubyte1_e32 v169, v223
	v_cvt_f32_ubyte2_e32 v170, v223
	v_cvt_f32_ubyte3_e32 v171, v223
	v_pk_add_f32 v[164:165], v[164:165], s[100:101]
	v_pk_add_f32 v[166:167], v[166:167], s[100:101]
	v_pk_add_f32 v[168:169], v[168:169], s[100:101]
	v_pk_add_f32 v[170:171], v[170:171], s[100:101]
	v_cvt_f32_ubyte0_e32 v154, v220
	v_cvt_f32_ubyte1_e32 v155, v220
	v_cvt_f32_ubyte2_e32 v156, v220
	v_cvt_f32_ubyte3_e32 v157, v220
	v_cvt_f32_ubyte0_e32 v160, v221
	v_cvt_f32_ubyte1_e32 v161, v221
	v_cvt_f32_ubyte2_e32 v162, v221
	v_cvt_f32_ubyte3_e32 v163, v221
	v_rcp_f32_e32 v164, v164
	v_rcp_f32_e32 v165, v165
	v_rcp_f32_e32 v166, v166
	v_rcp_f32_e32 v167, v167
	v_rcp_f32_e32 v168, v168
	v_rcp_f32_e32 v169, v169
	v_rcp_f32_e32 v170, v170
	v_rcp_f32_e32 v171, v171
	v_pk_add_f32 v[154:155], v[154:155], s[100:101]
	v_pk_add_f32 v[156:157], v[156:157], s[100:101]
	v_pk_add_f32 v[160:161], v[160:161], s[100:101]
	v_pk_add_f32 v[162:163], v[162:163], s[100:101]
	v_pk_mul_f32 v[154:155], v[154:155], v[164:165]
	v_pk_mul_f32 v[156:157], v[156:157], v[166:167]
	v_pk_mul_f32 v[160:161], v[160:161], v[168:169]
	v_pk_mul_f32 v[162:163], v[162:163], v[170:171]
	v_pk_mul_f32 v[70:71], v[70:71], v[154:155]
	v_pk_mul_f32 v[72:73], v[72:73], v[156:157]
	v_pk_mul_f32 v[66:67], v[66:67], v[160:161]
	v_pk_mul_f32 v[68:69], v[68:69], v[162:163]
	s_waitcnt vmcnt(14)
	v_cvt_f32_ubyte0_e32 v164, v226
	v_cvt_f32_ubyte1_e32 v165, v226
	v_cvt_f32_ubyte2_e32 v166, v226
	v_cvt_f32_ubyte3_e32 v167, v226
	v_cvt_f32_ubyte0_e32 v168, v227
	v_cvt_f32_ubyte1_e32 v169, v227
	v_cvt_f32_ubyte2_e32 v170, v227
	v_cvt_f32_ubyte3_e32 v171, v227
	v_pk_add_f32 v[164:165], v[164:165], s[100:101]
	v_pk_add_f32 v[166:167], v[166:167], s[100:101]
	v_pk_add_f32 v[168:169], v[168:169], s[100:101]
	v_pk_add_f32 v[170:171], v[170:171], s[100:101]
	v_cvt_f32_ubyte0_e32 v154, v224
	v_cvt_f32_ubyte1_e32 v155, v224
	v_cvt_f32_ubyte2_e32 v156, v224
	v_cvt_f32_ubyte3_e32 v157, v224
	v_cvt_f32_ubyte0_e32 v160, v225
	v_cvt_f32_ubyte1_e32 v161, v225
	v_cvt_f32_ubyte2_e32 v162, v225
	v_cvt_f32_ubyte3_e32 v163, v225
	v_rcp_f32_e32 v164, v164
	v_rcp_f32_e32 v165, v165
	v_rcp_f32_e32 v166, v166
	v_rcp_f32_e32 v167, v167
	v_rcp_f32_e32 v168, v168
	v_rcp_f32_e32 v169, v169
	v_rcp_f32_e32 v170, v170
	v_rcp_f32_e32 v171, v171
	v_pk_add_f32 v[154:155], v[154:155], s[100:101]
	v_pk_add_f32 v[156:157], v[156:157], s[100:101]
	v_pk_add_f32 v[160:161], v[160:161], s[100:101]
	v_pk_add_f32 v[162:163], v[162:163], s[100:101]
	v_pk_mul_f32 v[154:155], v[154:155], v[164:165]
	v_pk_mul_f32 v[156:157], v[156:157], v[166:167]
	v_pk_mul_f32 v[160:161], v[160:161], v[168:169]
	v_pk_mul_f32 v[162:163], v[162:163], v[170:171]
	v_pk_mul_f32 v[62:63], v[62:63], v[154:155]
	v_pk_mul_f32 v[64:65], v[64:65], v[156:157]
	v_pk_mul_f32 v[58:59], v[58:59], v[160:161]
	v_pk_mul_f32 v[60:61], v[60:61], v[162:163]
	s_waitcnt vmcnt(12)
	v_cvt_f32_ubyte0_e32 v164, v230
	v_cvt_f32_ubyte1_e32 v165, v230
	v_cvt_f32_ubyte2_e32 v166, v230
	v_cvt_f32_ubyte3_e32 v167, v230
	v_cvt_f32_ubyte0_e32 v168, v231
	v_cvt_f32_ubyte1_e32 v169, v231
	v_cvt_f32_ubyte2_e32 v170, v231
	v_cvt_f32_ubyte3_e32 v171, v231
	v_pk_add_f32 v[164:165], v[164:165], s[100:101]
	v_pk_add_f32 v[166:167], v[166:167], s[100:101]
	v_pk_add_f32 v[168:169], v[168:169], s[100:101]
	v_pk_add_f32 v[170:171], v[170:171], s[100:101]
	v_cvt_f32_ubyte0_e32 v154, v228
	v_cvt_f32_ubyte1_e32 v155, v228
	v_cvt_f32_ubyte2_e32 v156, v228
	v_cvt_f32_ubyte3_e32 v157, v228
	v_cvt_f32_ubyte0_e32 v160, v229
	v_cvt_f32_ubyte1_e32 v161, v229
	v_cvt_f32_ubyte2_e32 v162, v229
	v_cvt_f32_ubyte3_e32 v163, v229
	v_rcp_f32_e32 v164, v164
	v_rcp_f32_e32 v165, v165
	v_rcp_f32_e32 v166, v166
	v_rcp_f32_e32 v167, v167
	v_rcp_f32_e32 v168, v168
	v_rcp_f32_e32 v169, v169
	v_rcp_f32_e32 v170, v170
	v_rcp_f32_e32 v171, v171
	v_pk_add_f32 v[154:155], v[154:155], s[100:101]
	v_pk_add_f32 v[156:157], v[156:157], s[100:101]
	v_pk_add_f32 v[160:161], v[160:161], s[100:101]
	v_pk_add_f32 v[162:163], v[162:163], s[100:101]
	v_pk_mul_f32 v[154:155], v[154:155], v[164:165]
	v_pk_mul_f32 v[156:157], v[156:157], v[166:167]
	v_pk_mul_f32 v[160:161], v[160:161], v[168:169]
	v_pk_mul_f32 v[162:163], v[162:163], v[170:171]
	v_pk_mul_f32 v[30:31], v[30:31], v[154:155]
	v_pk_mul_f32 v[32:33], v[32:33], v[156:157]
	v_pk_mul_f32 v[26:27], v[26:27], v[160:161]
	v_pk_mul_f32 v[28:29], v[28:29], v[162:163]
	s_waitcnt vmcnt(10)
;     __device__ __forceinline__ void operator()(Acc& acc, const Unit& u, int wr, int wc, int fr, int fq) const {
;     ...
;                 for (int bj = 0; bj < 2; ++bj) { const int col = colb + bj * BJ; const unsigned char* gp = gates + (size_t)row * 6144 + j * 2048 + col;
;                     const u32x2 gw = *(const u32x2*)gp; const f32x4 g0 = unpack_gate4(gw.x), g1 = unpack_gate4(gw.y);
;                     if (j < 2) { const u32x2 hw = *(const u32x2*)(gp + 2048); const f32x4 h0 = unpack_gate4(hw.x), h1 = unpack_gate4(hw.y);
; #pragma unroll
;                         for (int e = 0; e < 4; ++e) { acc[ai][bj][m][0][e] *= g0[e] * __builtin_amdgcn_rcpf(fmaxf(h0[e], 1e-30f)); acc[ai][bj][m][1][e] *= g1[e] * __builtin_amdgcn_rcpf(fmaxf(h1[e], 1e-30f)); } }
	v_cvt_f32_ubyte0_e32 v164, v234
	v_cvt_f32_ubyte1_e32 v165, v234
	v_cvt_f32_ubyte2_e32 v166, v234
	v_cvt_f32_ubyte3_e32 v167, v234
	v_cvt_f32_ubyte0_e32 v168, v235
	v_cvt_f32_ubyte1_e32 v169, v235
	v_cvt_f32_ubyte2_e32 v170, v235
	v_cvt_f32_ubyte3_e32 v171, v235
	v_pk_add_f32 v[164:165], v[164:165], s[100:101]
	v_pk_add_f32 v[166:167], v[166:167], s[100:101]
	v_pk_add_f32 v[168:169], v[168:169], s[100:101]
	v_pk_add_f32 v[170:171], v[170:171], s[100:101]
	v_cvt_f32_ubyte0_e32 v154, v232
	v_cvt_f32_ubyte1_e32 v155, v232
	v_cvt_f32_ubyte2_e32 v156, v232
	v_cvt_f32_ubyte3_e32 v157, v232
	v_cvt_f32_ubyte0_e32 v160, v233
	v_cvt_f32_ubyte1_e32 v161, v233
	v_cvt_f32_ubyte2_e32 v162, v233
	v_cvt_f32_ubyte3_e32 v163, v233
	v_rcp_f32_e32 v164, v164
	v_rcp_f32_e32 v165, v165
	v_rcp_f32_e32 v166, v166
	v_rcp_f32_e32 v167, v167
	v_rcp_f32_e32 v168, v168
	v_rcp_f32_e32 v169, v169
	v_rcp_f32_e32 v170, v170
	v_rcp_f32_e32 v171, v171
	v_pk_add_f32 v[154:155], v[154:155], s[100:101]
	v_pk_add_f32 v[156:157], v[156:157], s[100:101]
	v_pk_add_f32 v[160:161], v[160:161], s[100:101]
	v_pk_add_f32 v[162:163], v[162:163], s[100:101]
	v_pk_mul_f32 v[154:155], v[154:155], v[164:165]
	v_pk_mul_f32 v[156:157], v[156:157], v[166:167]
	v_pk_mul_f32 v[160:161], v[160:161], v[168:169]
	v_pk_mul_f32 v[162:163], v[162:163], v[170:171]
	v_pk_mul_f32 v[54:55], v[54:55], v[154:155]
	v_pk_mul_f32 v[56:57], v[56:57], v[156:157]
	v_pk_mul_f32 v[50:51], v[50:51], v[160:161]
	v_pk_mul_f32 v[52:53], v[52:53], v[162:163]
	s_waitcnt vmcnt(8)
	v_cvt_f32_ubyte0_e32 v164, v238
	v_cvt_f32_ubyte1_e32 v165, v238
	v_cvt_f32_ubyte2_e32 v166, v238
	v_cvt_f32_ubyte3_e32 v167, v238
	v_cvt_f32_ubyte0_e32 v168, v239
	v_cvt_f32_ubyte1_e32 v169, v239
	v_cvt_f32_ubyte2_e32 v170, v239
	v_cvt_f32_ubyte3_e32 v171, v239
	v_pk_add_f32 v[164:165], v[164:165], s[100:101]
	v_pk_add_f32 v[166:167], v[166:167], s[100:101]
	v_pk_add_f32 v[168:169], v[168:169], s[100:101]
	v_pk_add_f32 v[170:171], v[170:171], s[100:101]
	v_cvt_f32_ubyte0_e32 v154, v236
	v_cvt_f32_ubyte1_e32 v155, v236
	v_cvt_f32_ubyte2_e32 v156, v236
	v_cvt_f32_ubyte3_e32 v157, v236
	v_cvt_f32_ubyte0_e32 v160, v237
	v_cvt_f32_ubyte1_e32 v161, v237
	v_cvt_f32_ubyte2_e32 v162, v237
	v_cvt_f32_ubyte3_e32 v163, v237
	v_rcp_f32_e32 v164, v164
	v_rcp_f32_e32 v165, v165
	v_rcp_f32_e32 v166, v166
	v_rcp_f32_e32 v167, v167
	v_rcp_f32_e32 v168, v168
	v_rcp_f32_e32 v169, v169
	v_rcp_f32_e32 v170, v170
	v_rcp_f32_e32 v171, v171
	v_pk_add_f32 v[154:155], v[154:155], s[100:101]
	v_pk_add_f32 v[156:157], v[156:157], s[100:101]
	v_pk_add_f32 v[160:161], v[160:161], s[100:101]
	v_pk_add_f32 v[162:163], v[162:163], s[100:101]
	v_pk_mul_f32 v[154:155], v[154:155], v[164:165]
	v_pk_mul_f32 v[156:157], v[156:157], v[166:167]
	v_pk_mul_f32 v[160:161], v[160:161], v[168:169]
	v_pk_mul_f32 v[162:163], v[162:163], v[170:171]
	v_pk_mul_f32 v[22:23], v[22:23], v[154:155]
	v_pk_mul_f32 v[24:25], v[24:25], v[156:157]
	v_pk_mul_f32 v[18:19], v[18:19], v[160:161]
	v_pk_mul_f32 v[20:21], v[20:21], v[162:163]
	s_waitcnt vmcnt(6)
	v_cvt_f32_ubyte0_e32 v164, v242
	v_cvt_f32_ubyte1_e32 v165, v242
	v_cvt_f32_ubyte2_e32 v166, v242
	v_cvt_f32_ubyte3_e32 v167, v242
	v_cvt_f32_ubyte0_e32 v168, v243
	v_cvt_f32_ubyte1_e32 v169, v243
	v_cvt_f32_ubyte2_e32 v170, v243
	v_cvt_f32_ubyte3_e32 v171, v243
	v_pk_add_f32 v[164:165], v[164:165], s[100:101]
	v_pk_add_f32 v[166:167], v[166:167], s[100:101]
	v_pk_add_f32 v[168:169], v[168:169], s[100:101]
	v_pk_add_f32 v[170:171], v[170:171], s[100:101]
	v_cvt_f32_ubyte0_e32 v154, v240
	v_cvt_f32_ubyte1_e32 v155, v240
	v_cvt_f32_ubyte2_e32 v156, v240
	v_cvt_f32_ubyte3_e32 v157, v240
	v_cvt_f32_ubyte0_e32 v160, v241
	v_cvt_f32_ubyte1_e32 v161, v241
	v_cvt_f32_ubyte2_e32 v162, v241
	v_cvt_f32_ubyte3_e32 v163, v241
	v_rcp_f32_e32 v164, v164
	v_rcp_f32_e32 v165, v165
	v_rcp_f32_e32 v166, v166
	v_rcp_f32_e32 v167, v167
	v_rcp_f32_e32 v168, v168
	v_rcp_f32_e32 v169, v169
	v_rcp_f32_e32 v170, v170
	v_rcp_f32_e32 v171, v171
	v_pk_add_f32 v[154:155], v[154:155], s[100:101]
	v_pk_add_f32 v[156:157], v[156:157], s[100:101]
	v_pk_add_f32 v[160:161], v[160:161], s[100:101]
	v_pk_add_f32 v[162:163], v[162:163], s[100:101]
	v_pk_mul_f32 v[154:155], v[154:155], v[164:165]
	v_pk_mul_f32 v[156:157], v[156:157], v[166:167]
	v_pk_mul_f32 v[160:161], v[160:161], v[168:169]
	v_pk_mul_f32 v[162:163], v[162:163], v[170:171]
	v_pk_mul_f32 v[46:47], v[46:47], v[154:155]
	v_pk_mul_f32 v[48:49], v[48:49], v[156:157]
	v_pk_mul_f32 v[42:43], v[42:43], v[160:161]
	v_pk_mul_f32 v[44:45], v[44:45], v[162:163]
	s_waitcnt vmcnt(4)
;     __device__ __forceinline__ void operator()(Acc& acc, const Unit& u, int wr, int wc, int fr, int fq) const {
;     ...
;                 for (int bj = 0; bj < 2; ++bj) { const int col = colb + bj * BJ; const unsigned char* gp = gates + (size_t)row * 6144 + j * 2048 + col;
;                     const u32x2 gw = *(const u32x2*)gp; const f32x4 g0 = unpack_gate4(gw.x), g1 = unpack_gate4(gw.y);
;                     if (j < 2) { const u32x2 hw = *(const u32x2*)(gp + 2048); const f32x4 h0 = unpack_gate4(hw.x), h1 = unpack_gate4(hw.y);
; #pragma unroll
;                         for (int e = 0; e < 4; ++e) { acc[ai][bj][m][0][e] *= g0[e] * __builtin_amdgcn_rcpf(fmaxf(h0[e], 1e-30f)); acc[ai][bj][m][1][e] *= g1[e] * __builtin_amdgcn_rcpf(fmaxf(h1[e], 1e-30f)); } }
	v_cvt_f32_ubyte0_e32 v164, v246
	v_cvt_f32_ubyte1_e32 v165, v246
	v_cvt_f32_ubyte2_e32 v166, v246
	v_cvt_f32_ubyte3_e32 v167, v246
	v_cvt_f32_ubyte0_e32 v168, v247
	v_cvt_f32_ubyte1_e32 v169, v247
	v_cvt_f32_ubyte2_e32 v170, v247
	v_cvt_f32_ubyte3_e32 v171, v247
	v_pk_add_f32 v[164:165], v[164:165], s[100:101]
	v_pk_add_f32 v[166:167], v[166:167], s[100:101]
	v_pk_add_f32 v[168:169], v[168:169], s[100:101]
	v_pk_add_f32 v[170:171], v[170:171], s[100:101]
	v_cvt_f32_ubyte0_e32 v154, v244
	v_cvt_f32_ubyte1_e32 v155, v244
	v_cvt_f32_ubyte2_e32 v156, v244
	v_cvt_f32_ubyte3_e32 v157, v244
	v_cvt_f32_ubyte0_e32 v160, v245
	v_cvt_f32_ubyte1_e32 v161, v245
	v_cvt_f32_ubyte2_e32 v162, v245
	v_cvt_f32_ubyte3_e32 v163, v245
	v_rcp_f32_e32 v164, v164
	v_rcp_f32_e32 v165, v165
	v_rcp_f32_e32 v166, v166
	v_rcp_f32_e32 v167, v167
	v_rcp_f32_e32 v168, v168
	v_rcp_f32_e32 v169, v169
	v_rcp_f32_e32 v170, v170
	v_rcp_f32_e32 v171, v171
	v_pk_add_f32 v[154:155], v[154:155], s[100:101]
	v_pk_add_f32 v[156:157], v[156:157], s[100:101]
	v_pk_add_f32 v[160:161], v[160:161], s[100:101]
	v_pk_add_f32 v[162:163], v[162:163], s[100:101]
	v_pk_mul_f32 v[154:155], v[154:155], v[164:165]
	v_pk_mul_f32 v[156:157], v[156:157], v[166:167]
	v_pk_mul_f32 v[160:161], v[160:161], v[168:169]
	v_pk_mul_f32 v[162:163], v[162:163], v[170:171]
	v_pk_mul_f32 v[14:15], v[14:15], v[154:155]
	v_pk_mul_f32 v[16:17], v[16:17], v[156:157]
	v_pk_mul_f32 v[10:11], v[10:11], v[160:161]
	v_pk_mul_f32 v[12:13], v[12:13], v[162:163]
	s_waitcnt vmcnt(2)
	v_cvt_f32_ubyte0_e32 v164, v174
	v_cvt_f32_ubyte1_e32 v165, v174
	v_cvt_f32_ubyte2_e32 v166, v174
	v_cvt_f32_ubyte3_e32 v167, v174
	v_cvt_f32_ubyte0_e32 v168, v175
	v_cvt_f32_ubyte1_e32 v169, v175
	v_cvt_f32_ubyte2_e32 v170, v175
	v_cvt_f32_ubyte3_e32 v171, v175
	v_pk_add_f32 v[164:165], v[164:165], s[100:101]
	v_pk_add_f32 v[166:167], v[166:167], s[100:101]
	v_pk_add_f32 v[168:169], v[168:169], s[100:101]
	v_pk_add_f32 v[170:171], v[170:171], s[100:101]
	v_cvt_f32_ubyte0_e32 v154, v172
	v_cvt_f32_ubyte1_e32 v155, v172
	v_cvt_f32_ubyte2_e32 v156, v172
	v_cvt_f32_ubyte3_e32 v157, v172
	v_cvt_f32_ubyte0_e32 v160, v173
	v_cvt_f32_ubyte1_e32 v161, v173
	v_cvt_f32_ubyte2_e32 v162, v173
	v_cvt_f32_ubyte3_e32 v163, v173
	v_rcp_f32_e32 v164, v164
	v_rcp_f32_e32 v165, v165
	v_rcp_f32_e32 v166, v166
	v_rcp_f32_e32 v167, v167
	v_rcp_f32_e32 v168, v168
	v_rcp_f32_e32 v169, v169
	v_rcp_f32_e32 v170, v170
	v_rcp_f32_e32 v171, v171
	v_pk_add_f32 v[154:155], v[154:155], s[100:101]
	v_pk_add_f32 v[156:157], v[156:157], s[100:101]
	v_pk_add_f32 v[160:161], v[160:161], s[100:101]
	v_pk_add_f32 v[162:163], v[162:163], s[100:101]
	v_pk_mul_f32 v[154:155], v[154:155], v[164:165]
	v_pk_mul_f32 v[156:157], v[156:157], v[166:167]
	v_pk_mul_f32 v[160:161], v[160:161], v[168:169]
	v_pk_mul_f32 v[162:163], v[162:163], v[170:171]
	v_pk_mul_f32 v[38:39], v[38:39], v[154:155]
	v_pk_mul_f32 v[40:41], v[40:41], v[156:157]
	v_pk_mul_f32 v[34:35], v[34:35], v[160:161]
	v_pk_mul_f32 v[36:37], v[36:37], v[162:163]
	s_waitcnt vmcnt(0)
	v_cvt_f32_ubyte0_e32 v164, v180
	v_cvt_f32_ubyte1_e32 v165, v180
	v_cvt_f32_ubyte2_e32 v166, v180
	v_cvt_f32_ubyte3_e32 v167, v180
	v_cvt_f32_ubyte0_e32 v168, v181
	v_cvt_f32_ubyte1_e32 v169, v181
	v_cvt_f32_ubyte2_e32 v170, v181
	v_cvt_f32_ubyte3_e32 v171, v181
	v_pk_add_f32 v[164:165], v[164:165], s[100:101]
	v_pk_add_f32 v[166:167], v[166:167], s[100:101]
	v_pk_add_f32 v[168:169], v[168:169], s[100:101]
	v_pk_add_f32 v[170:171], v[170:171], s[100:101]
	v_cvt_f32_ubyte0_e32 v154, v176
	v_cvt_f32_ubyte1_e32 v155, v176
	v_cvt_f32_ubyte2_e32 v156, v176
	v_cvt_f32_ubyte3_e32 v157, v176
	v_cvt_f32_ubyte0_e32 v160, v177
	v_cvt_f32_ubyte1_e32 v161, v177
	v_cvt_f32_ubyte2_e32 v162, v177
	v_cvt_f32_ubyte3_e32 v163, v177
	v_rcp_f32_e32 v164, v164
	v_rcp_f32_e32 v165, v165
	v_rcp_f32_e32 v166, v166
	v_rcp_f32_e32 v167, v167
	v_rcp_f32_e32 v168, v168
	v_rcp_f32_e32 v169, v169
	v_rcp_f32_e32 v170, v170
	v_rcp_f32_e32 v171, v171
	v_pk_add_f32 v[154:155], v[154:155], s[100:101]
	v_pk_add_f32 v[156:157], v[156:157], s[100:101]
	v_pk_add_f32 v[160:161], v[160:161], s[100:101]
	v_pk_add_f32 v[162:163], v[162:163], s[100:101]
	v_pk_mul_f32 v[154:155], v[154:155], v[164:165]
	v_pk_mul_f32 v[156:157], v[156:157], v[166:167]
	v_pk_mul_f32 v[160:161], v[160:161], v[168:169]
	v_pk_mul_f32 v[162:163], v[162:163], v[170:171]
	v_pk_mul_f32 v[6:7], v[6:7], v[154:155]
	v_pk_mul_f32 v[8:9], v[8:9], v[156:157]
	v_pk_mul_f32 v[2:3], v[2:3], v[160:161]
	v_pk_mul_f32 v[4:5], v[4:5], v[162:163]
	s_mov_b64 s[72:73], -1
	s_andn2_b64 vcc, exec, s[0:1]
	s_mov_b64 s[0:1], -1
	s_cbranch_vccnz .LBB0_700
	s_branch .LBB0_776
